# P7 out-proj GEMM K-loop: LDS-DMA loads in SGPR-base + 32-bit VGPR-offset form (16 64-bit VALU adds per iteration removed)
# baseline (speedup 1.0000x reference)
.LBB0_900:
	ds_read_b128 v[148:151], v145
	ds_read_b128 v[152:155], v145 offset:1024
	ds_read_b128 v[156:159], v145 offset:2048
	ds_read_b128 v[160:163], v145 offset:3072
	ds_read_b128 v[164:167], v146
	ds_read_b128 v[168:171], v146 offset:1024
	ds_read_b128 v[172:175], v146 offset:2048
	ds_read_b128 v[176:179], v146 offset:3072
	s_add_i32 s76, s28, 2
	s_add_u32 s29, s10, 0xfffc0080
	s_addc_u32 s36, s11, -1
	s_cmp_eq_u32 s67, s28
	s_cselect_b32 s28, s73, s74
	s_cselect_b32 s37, s43, s36
	s_cselect_b32 s36, s45, s29
	s_cselect_b32 s29, s72, s75
	v_lshl_add_u64 v[188:189], s[10:11], 0, v[136:137]
	s_add_i32 m0, s58, 0xc000
	ds_read_b128 v[180:183], v147
	ds_read_b128 v[184:187], v147 offset:1024
	ds_read_b128 v[192:195], v147 offset:2048
	ds_read_b128 v[196:199], v147 offset:3072
	ds_read_b128 v[200:203], v147 offset:4096
	ds_read_b128 v[204:207], v147 offset:5120
	ds_read_b128 v[208:211], v147 offset:6144
	ds_read_b128 v[212:215], v147 offset:7168
	global_load_lds_dwordx4 v[188:189], off
	v_lshl_add_u64 v[188:189], s[10:11], 0, v[138:139]
	s_add_i32 m0, s58, 0xe000
	s_nop 0
	global_load_lds_dwordx4 v[188:189], off
	s_waitcnt vmcnt(8)
	s_waitcnt lgkmcnt(0)
	s_barrier
	s_setprio 1
	s_waitcnt lgkmcnt(0)
	v_mfma_f32_16x16x32_bf16 v[124:127], v[148:151], v[180:183], v[124:127]
	v_mfma_f32_16x16x32_bf16 v[120:123], v[156:159], v[180:183], v[120:123]
	v_mfma_f32_16x16x32_bf16 v[116:119], v[148:151], v[192:195], v[116:119]
	v_mfma_f32_16x16x32_bf16 v[112:115], v[156:159], v[192:195], v[112:115]
	v_mfma_f32_16x16x32_bf16 v[108:111], v[148:151], v[200:203], v[108:111]
	v_mfma_f32_16x16x32_bf16 v[104:107], v[156:159], v[200:203], v[104:107]
	v_mfma_f32_16x16x32_bf16 v[100:103], v[148:151], v[208:211], v[100:103]
	v_mfma_f32_16x16x32_bf16 v[96:99], v[156:159], v[208:211], v[96:99]
	v_mfma_f32_16x16x32_bf16 v[124:127], v[152:155], v[184:187], v[124:127]
	v_mfma_f32_16x16x32_bf16 v[120:123], v[160:163], v[184:187], v[120:123]
	v_mfma_f32_16x16x32_bf16 v[116:119], v[152:155], v[196:199], v[116:119]
	v_mfma_f32_16x16x32_bf16 v[112:115], v[160:163], v[196:199], v[112:115]
	v_mfma_f32_16x16x32_bf16 v[108:111], v[152:155], v[204:207], v[108:111]
	v_mfma_f32_16x16x32_bf16 v[104:107], v[160:163], v[204:207], v[104:107]
	v_mfma_f32_16x16x32_bf16 v[100:103], v[152:155], v[212:215], v[100:103]
	v_mfma_f32_16x16x32_bf16 v[96:99], v[160:163], v[212:215], v[96:99]
	s_setprio 0
	s_setprio 1
	v_mfma_f32_16x16x32_bf16 v[60:63], v[164:167], v[180:183], v[60:63]
	v_mfma_f32_16x16x32_bf16 v[56:59], v[172:175], v[180:183], v[56:59]
	v_mfma_f32_16x16x32_bf16 v[52:55], v[164:167], v[192:195], v[52:55]
	v_mfma_f32_16x16x32_bf16 v[48:51], v[172:175], v[192:195], v[48:51]
	v_mfma_f32_16x16x32_bf16 v[44:47], v[164:167], v[200:203], v[44:47]
	v_mfma_f32_16x16x32_bf16 v[40:43], v[172:175], v[200:203], v[40:43]
	v_mfma_f32_16x16x32_bf16 v[36:39], v[164:167], v[208:211], v[36:39]
	v_mfma_f32_16x16x32_bf16 v[32:35], v[172:175], v[208:211], v[32:35]
	v_mfma_f32_16x16x32_bf16 v[60:63], v[168:171], v[184:187], v[60:63]
	v_mfma_f32_16x16x32_bf16 v[56:59], v[176:179], v[184:187], v[56:59]
	v_mfma_f32_16x16x32_bf16 v[52:55], v[168:171], v[196:199], v[52:55]
	v_mfma_f32_16x16x32_bf16 v[48:51], v[176:179], v[196:199], v[48:51]
	v_mfma_f32_16x16x32_bf16 v[44:47], v[168:171], v[204:207], v[44:47]
	v_mfma_f32_16x16x32_bf16 v[40:43], v[176:179], v[204:207], v[40:43]
	v_mfma_f32_16x16x32_bf16 v[36:39], v[168:171], v[212:215], v[36:39]
	v_mfma_f32_16x16x32_bf16 v[32:35], v[176:179], v[212:215], v[32:35]
	s_setprio 0
	s_barrier
	s_add_i32 s77, s70, s57
	s_mov_b32 m0, s77
	ds_read_b128 v[180:183], v147 offset:16384
	ds_read_b128 v[184:187], v147 offset:17408
	ds_read_b128 v[192:195], v147 offset:18432
	ds_read_b128 v[196:199], v147 offset:19456
	ds_read_b128 v[200:203], v147 offset:20480
	ds_read_b128 v[204:207], v147 offset:21504
	ds_read_b128 v[208:211], v147 offset:22528
	ds_read_b128 v[212:215], v147 offset:23552
	global_load_lds_dwordx4 v130, s[28:29]
	s_add_i32 m0, s77, 0x2000
	s_add_u32 s78, s28, 0x40000
	s_addc_u32 s79, s29, 0
	s_add_i32 s77, s71, s57
	global_load_lds_dwordx4 v134, s[28:29]
	s_mov_b32 m0, s77
	s_mov_b64 s[98:99], s[36:37]
	global_load_lds_dwordx4 v130, s[78:79]
	s_add_i32 m0, s77, 0x2000
	s_nop 0
	global_load_lds_dwordx4 v134, s[78:79]
	s_mov_b32 m0, s58
	s_nop 0
	global_load_lds_dwordx4 v128, s[36:37]
	s_mov_b32 m0, s59
	s_nop 0
	global_load_lds_dwordx4 v132, s[36:37]
	s_waitcnt vmcnt(8)
	s_waitcnt lgkmcnt(0)
	s_barrier
	s_setprio 1
	s_waitcnt lgkmcnt(0)
	v_mfma_f32_16x16x32_bf16 v[92:95], v[148:151], v[180:183], v[92:95]
	v_mfma_f32_16x16x32_bf16 v[88:91], v[156:159], v[180:183], v[88:91]
	v_mfma_f32_16x16x32_bf16 v[84:87], v[148:151], v[192:195], v[84:87]
	v_mfma_f32_16x16x32_bf16 v[80:83], v[156:159], v[192:195], v[80:83]
	v_mfma_f32_16x16x32_bf16 v[76:79], v[148:151], v[200:203], v[76:79]
	v_mfma_f32_16x16x32_bf16 v[72:75], v[156:159], v[200:203], v[72:75]
	v_mfma_f32_16x16x32_bf16 v[68:71], v[148:151], v[208:211], v[68:71]
	v_mfma_f32_16x16x32_bf16 v[64:67], v[156:159], v[208:211], v[64:67]
	v_mfma_f32_16x16x32_bf16 v[92:95], v[152:155], v[184:187], v[92:95]
	v_mfma_f32_16x16x32_bf16 v[88:91], v[160:163], v[184:187], v[88:91]
	v_mfma_f32_16x16x32_bf16 v[84:87], v[152:155], v[196:199], v[84:87]
	v_mfma_f32_16x16x32_bf16 v[80:83], v[160:163], v[196:199], v[80:83]
	v_mfma_f32_16x16x32_bf16 v[76:79], v[152:155], v[204:207], v[76:79]
	v_mfma_f32_16x16x32_bf16 v[72:75], v[160:163], v[204:207], v[72:75]
	v_mfma_f32_16x16x32_bf16 v[68:71], v[152:155], v[212:215], v[68:71]
	v_mfma_f32_16x16x32_bf16 v[64:67], v[160:163], v[212:215], v[64:67]
	s_setprio 0
	s_setprio 1
	v_mfma_f32_16x16x32_bf16 v[28:31], v[164:167], v[180:183], v[28:31]
	v_mfma_f32_16x16x32_bf16 v[24:27], v[172:175], v[180:183], v[24:27]
	v_mfma_f32_16x16x32_bf16 v[20:23], v[164:167], v[192:195], v[20:23]
	v_mfma_f32_16x16x32_bf16 v[16:19], v[172:175], v[192:195], v[16:19]
	v_mfma_f32_16x16x32_bf16 v[12:15], v[164:167], v[200:203], v[12:15]
	v_mfma_f32_16x16x32_bf16 v[8:11], v[172:175], v[200:203], v[8:11]
	v_mfma_f32_16x16x32_bf16 v[4:7], v[164:167], v[208:211], v[4:7]
	v_mfma_f32_16x16x32_bf16 v[0:3], v[172:175], v[208:211], v[0:3]
	v_mfma_f32_16x16x32_bf16 v[28:31], v[168:171], v[184:187], v[28:31]
	v_mfma_f32_16x16x32_bf16 v[24:27], v[176:179], v[184:187], v[24:27]
	v_mfma_f32_16x16x32_bf16 v[20:23], v[168:171], v[196:199], v[20:23]
	v_mfma_f32_16x16x32_bf16 v[16:19], v[176:179], v[196:199], v[16:19]
	v_mfma_f32_16x16x32_bf16 v[12:15], v[168:171], v[204:207], v[12:15]
	v_mfma_f32_16x16x32_bf16 v[8:11], v[176:179], v[204:207], v[8:11]
	v_mfma_f32_16x16x32_bf16 v[4:7], v[168:171], v[212:215], v[4:7]
	v_mfma_f32_16x16x32_bf16 v[0:3], v[176:179], v[212:215], v[0:3]
	s_setprio 0
	s_barrier
	s_add_i32 s77, 0, 0x18000
	s_add_i32 s78, 0, 0x1c000
	v_add_u32_e32 v160, s77, v144
	v_add_u32_e32 v176, s78, v144
	ds_read_b128 v[148:151], v160
	ds_read_b128 v[152:155], v160 offset:1024
	ds_read_b128 v[156:159], v160 offset:2048
	ds_read_b128 v[160:163], v160 offset:3072
	ds_read_b128 v[164:167], v176
	ds_read_b128 v[168:171], v176 offset:1024
	ds_read_b128 v[172:175], v176 offset:2048
	ds_read_b128 v[176:179], v176 offset:3072
	s_add_u32 s36, s36, 0x40000
	s_addc_u32 s37, s37, 0
	s_mov_b32 m0, s60
	ds_read_b128 v[180:183], v147 offset:32768
	ds_read_b128 v[184:187], v147 offset:33792
	ds_read_b128 v[192:195], v147 offset:34816
	ds_read_b128 v[196:199], v147 offset:35840
	ds_read_b128 v[200:203], v147 offset:36864
	ds_read_b128 v[204:207], v147 offset:37888
	ds_read_b128 v[208:211], v147 offset:38912
	ds_read_b128 v[212:215], v147 offset:39936
	global_load_lds_dwordx4 v128, s[36:37]
	s_mov_b32 m0, s61
	s_nop 0
	global_load_lds_dwordx4 v132, s[36:37]
	s_waitcnt vmcnt(8)
	s_waitcnt lgkmcnt(0)
	s_barrier
	s_setprio 1
	s_waitcnt lgkmcnt(0)
	v_mfma_f32_16x16x32_bf16 v[124:127], v[148:151], v[180:183], v[124:127]
	v_mfma_f32_16x16x32_bf16 v[120:123], v[156:159], v[180:183], v[120:123]
	v_mfma_f32_16x16x32_bf16 v[116:119], v[148:151], v[192:195], v[116:119]
	v_mfma_f32_16x16x32_bf16 v[112:115], v[156:159], v[192:195], v[112:115]
	v_mfma_f32_16x16x32_bf16 v[108:111], v[148:151], v[200:203], v[108:111]
	v_mfma_f32_16x16x32_bf16 v[104:107], v[156:159], v[200:203], v[104:107]
	v_mfma_f32_16x16x32_bf16 v[100:103], v[148:151], v[208:211], v[100:103]
	v_mfma_f32_16x16x32_bf16 v[96:99], v[156:159], v[208:211], v[96:99]
	v_mfma_f32_16x16x32_bf16 v[124:127], v[152:155], v[184:187], v[124:127]
	v_mfma_f32_16x16x32_bf16 v[120:123], v[160:163], v[184:187], v[120:123]
	v_mfma_f32_16x16x32_bf16 v[116:119], v[152:155], v[196:199], v[116:119]
	v_mfma_f32_16x16x32_bf16 v[112:115], v[160:163], v[196:199], v[112:115]
	v_mfma_f32_16x16x32_bf16 v[108:111], v[152:155], v[204:207], v[108:111]
	v_mfma_f32_16x16x32_bf16 v[104:107], v[160:163], v[204:207], v[104:107]
	v_mfma_f32_16x16x32_bf16 v[100:103], v[152:155], v[212:215], v[100:103]
	v_mfma_f32_16x16x32_bf16 v[96:99], v[160:163], v[212:215], v[96:99]
	s_setprio 0
	s_setprio 1
	v_mfma_f32_16x16x32_bf16 v[60:63], v[164:167], v[180:183], v[60:63]
	v_mfma_f32_16x16x32_bf16 v[56:59], v[172:175], v[180:183], v[56:59]
	v_mfma_f32_16x16x32_bf16 v[52:55], v[164:167], v[192:195], v[52:55]
	v_mfma_f32_16x16x32_bf16 v[48:51], v[172:175], v[192:195], v[48:51]
	v_mfma_f32_16x16x32_bf16 v[44:47], v[164:167], v[200:203], v[44:47]
	v_mfma_f32_16x16x32_bf16 v[40:43], v[172:175], v[200:203], v[40:43]
	v_mfma_f32_16x16x32_bf16 v[36:39], v[164:167], v[208:211], v[36:39]
	v_mfma_f32_16x16x32_bf16 v[32:35], v[172:175], v[208:211], v[32:35]
	v_mfma_f32_16x16x32_bf16 v[60:63], v[168:171], v[184:187], v[60:63]
	v_mfma_f32_16x16x32_bf16 v[56:59], v[176:179], v[184:187], v[56:59]
	v_mfma_f32_16x16x32_bf16 v[52:55], v[168:171], v[196:199], v[52:55]
	v_mfma_f32_16x16x32_bf16 v[48:51], v[176:179], v[196:199], v[48:51]
	v_mfma_f32_16x16x32_bf16 v[44:47], v[168:171], v[204:207], v[44:47]
	v_mfma_f32_16x16x32_bf16 v[40:43], v[176:179], v[204:207], v[40:43]
	v_mfma_f32_16x16x32_bf16 v[36:39], v[168:171], v[212:215], v[36:39]
	v_mfma_f32_16x16x32_bf16 v[32:35], v[176:179], v[212:215], v[32:35]
	s_setprio 0
	s_barrier
	s_add_i32 s36, s77, s57
	s_add_i32 m0, s36, 0xffffff80
	ds_read_b128 v[180:183], v147 offset:49152
	ds_read_b128 v[184:187], v147 offset:50176
	ds_read_b128 v[192:195], v147 offset:51200
	ds_read_b128 v[196:199], v147 offset:52224
	ds_read_b128 v[200:203], v147 offset:53248
	ds_read_b128 v[204:207], v147 offset:54272
	ds_read_b128 v[208:211], v147 offset:55296
	ds_read_b128 v[212:215], v147 offset:56320
	global_load_lds_dwordx4 v130, s[28:29] offset:128
	s_add_i32 m0, s36, 0x1f80
	s_add_i32 s36, s78, s57
	global_load_lds_dwordx4 v134, s[28:29] offset:128
	s_add_u32 s28, s28, 0x40080
	s_addc_u32 s29, s29, 0
	s_mov_b32 m0, s36
	s_nop 0
	global_load_lds_dwordx4 v130, s[28:29]
	s_add_i32 m0, s36, 0x2000
	s_nop 0
	global_load_lds_dwordx4 v134, s[28:29]
	s_add_i32 m0, s65, 0xffffff80
	s_nop 0
	global_load_lds_dwordx4 v128, s[98:99] offset:128
	s_add_i32 m0, s66, 0xffffff80
	s_nop 0
	global_load_lds_dwordx4 v132, s[98:99] offset:128
	s_waitcnt vmcnt(8)
	s_waitcnt lgkmcnt(0)
	s_barrier
	s_setprio 1
	s_waitcnt lgkmcnt(0)
	v_mfma_f32_16x16x32_bf16 v[92:95], v[148:151], v[180:183], v[92:95]
	v_mfma_f32_16x16x32_bf16 v[88:91], v[156:159], v[180:183], v[88:91]
	v_mfma_f32_16x16x32_bf16 v[84:87], v[148:151], v[192:195], v[84:87]
	v_mfma_f32_16x16x32_bf16 v[80:83], v[156:159], v[192:195], v[80:83]
	v_mfma_f32_16x16x32_bf16 v[76:79], v[148:151], v[200:203], v[76:79]
	v_mfma_f32_16x16x32_bf16 v[72:75], v[156:159], v[200:203], v[72:75]
	v_mfma_f32_16x16x32_bf16 v[68:71], v[148:151], v[208:211], v[68:71]
	v_mfma_f32_16x16x32_bf16 v[64:67], v[156:159], v[208:211], v[64:67]
	v_mfma_f32_16x16x32_bf16 v[92:95], v[152:155], v[184:187], v[92:95]
	v_mfma_f32_16x16x32_bf16 v[88:91], v[160:163], v[184:187], v[88:91]
	v_mfma_f32_16x16x32_bf16 v[84:87], v[152:155], v[196:199], v[84:87]
	v_mfma_f32_16x16x32_bf16 v[80:83], v[160:163], v[196:199], v[80:83]
	v_mfma_f32_16x16x32_bf16 v[76:79], v[152:155], v[204:207], v[76:79]
	v_mfma_f32_16x16x32_bf16 v[72:75], v[160:163], v[204:207], v[72:75]
	v_mfma_f32_16x16x32_bf16 v[68:71], v[152:155], v[212:215], v[68:71]
	v_mfma_f32_16x16x32_bf16 v[64:67], v[160:163], v[212:215], v[64:67]
	s_setprio 0
	s_setprio 1
	v_mfma_f32_16x16x32_bf16 v[28:31], v[164:167], v[180:183], v[28:31]
	v_mfma_f32_16x16x32_bf16 v[24:27], v[172:175], v[180:183], v[24:27]
	v_mfma_f32_16x16x32_bf16 v[20:23], v[164:167], v[192:195], v[20:23]
	v_mfma_f32_16x16x32_bf16 v[16:19], v[172:175], v[192:195], v[16:19]
	v_mfma_f32_16x16x32_bf16 v[12:15], v[164:167], v[200:203], v[12:15]
	v_mfma_f32_16x16x32_bf16 v[8:11], v[172:175], v[200:203], v[8:11]
	v_mfma_f32_16x16x32_bf16 v[4:7], v[164:167], v[208:211], v[4:7]
	v_mfma_f32_16x16x32_bf16 v[0:3], v[172:175], v[208:211], v[0:3]
	v_mfma_f32_16x16x32_bf16 v[28:31], v[168:171], v[184:187], v[28:31]
	v_mfma_f32_16x16x32_bf16 v[24:27], v[176:179], v[184:187], v[24:27]
	v_mfma_f32_16x16x32_bf16 v[20:23], v[168:171], v[196:199], v[20:23]
	v_mfma_f32_16x16x32_bf16 v[16:19], v[176:179], v[196:199], v[16:19]
	v_mfma_f32_16x16x32_bf16 v[12:15], v[168:171], v[204:207], v[12:15]
	v_mfma_f32_16x16x32_bf16 v[8:11], v[176:179], v[204:207], v[8:11]
	v_mfma_f32_16x16x32_bf16 v[4:7], v[168:171], v[212:215], v[4:7]
	v_mfma_f32_16x16x32_bf16 v[0:3], v[176:179], v[212:215], v[0:3]
	s_setprio 0
	s_barrier
	s_add_u32 s10, s10, 0x100
	s_addc_u32 s11, s11, 0
	s_add_u32 s74, s74, 0x100
	s_addc_u32 s75, s75, 0
	s_cmp_ge_i32 s76, s3
	s_mov_b32 s28, s76
	s_cbranch_scc0 .LBB0_900
	s_and_b64 vcc, exec, s[40:41]
	s_cbranch_vccz .LBB0_903
